# fetch waves: V rows prefetched two trips ahead and issued behind the slot batch; DONE atomics issued after the slot-0 batch
# speedup vs baseline: 1.0074x; 1.0074x over previous
; #define RD_PEEK(cc) __hip_atomic_load(READY + bh * 512 + (cc), __ATOMIC_RELAXED, __HIP_MEMORY_SCOPE_AGENT)
; __device__ void phase_rwkv_dist(const Params& p, LAS unsigned char* lds, int wg, int nwg) {
;     ...
;             bf16_t* SS = (bf16_t*)p.out; const float* CD = (const float*)(p.ws + WS_CTL + WS_CD);
;             const int nitem = (BATCH * 32 * 64 * 32 + nwg * 64 - 1) / (nwg * 64), nstep = ((nitem + 3) / 4) * 128;
;             const int per = (nitem + 3) / 4;
;             int s2 = (unit == wg) ? 0 : nstep; f32x4 hh = zero4;
;             RD_ISSUE(fw, 0, 0u);
;             for (int c2 = fw; c2 < RC_NCHK; c2 += 8) {
;                 const unsigned pr1 = RD_PEEK(c2 + 4), pr0 = (c2 + 8 < RC_NCHK) ? RD_PEEK(c2 + 8) : 0u;
;                 u32x2 raw[4]; float dd[4]; bf16_t* qq[4]; bool ok[4];
; #pragma unroll
;                 for (int k = 0; k < 4; ++k) { const int ss = s2 + k, item = fw * per + (ss >> 7), cc = ss & 127, idx = item * (nwg * 64) + wg * 64 + lane; ok[k] = ss < nstep && (ss >> 7) < per && item < nitem && idx < BATCH * 32 * 64 * 32;
;                     const int n4 = idx & 31, pp = (idx >> 5) & 63, eg = (idx >> 11) & 31, bb = idx >> 16;
;                     qq[k] = SS + ((((size_t)bb * 128 + cc) * 32 + eg) * 64 + pp) * 128 + 4 * n4; raw[k] = (u32x2){0u, 0u}; dd[k] = 0.f;
;                     if (ok[k]) { raw[k] = *(const u32x2*)qq[k]; dd[k] = CD[(bb * 128 + cc) * 32 + eg]; } }
.LBB0_681:
	v_readlane_b32 s6, v253, 51
	s_cmp_lg_u32 s51, s6
	v_readlane_b32 s6, v254, 18
	v_readlane_b32 s7, v254, 19
	s_cselect_b32 s81, s56, 0
	s_andn2_b64 vcc, exec, s[6:7]
	s_cbranch_vccnz .LBB0_769
	v_writelane_b32 v254, s72, 46
	s_lshl_b32 s84, s94, 20
	v_readlane_b32 s6, v254, 14
	s_add_i32 s6, s80, s6
	s_add_i32 s7, s6, 0x2000
	buffer_load_dwordx4 v[80:83], v197, s[52:55], s7 offen sc1
	buffer_load_dwordx4 v[72:75], v196, s[52:55], s7 offen sc1
	s_add_i32 s7, s6, 0x1000
	buffer_load_dwordx4 v[88:91], v215, s[52:55], s7 offen sc1
	buffer_load_dwordx4 v[84:87], v213, s[52:55], s7 offen sc1
	buffer_load_dwordx4 v[96:99], v197, s[52:55], s7 offen sc1
	buffer_load_dwordx4 v[92:95], v196, s[52:55], s7 offen sc1
	buffer_load_dwordx4 v[64:67], v215, s[52:55], s6 offen sc1
	buffer_load_dwordx4 v[60:63], v213, s[52:55], s6 offen sc1
	buffer_load_dwordx4 v[68:71], v197, s[52:55], s6 offen sc1
	buffer_load_dwordx4 v[76:79], v196, s[52:55], s6 offen sc1
	v_readlane_b32 s7, v254, 16
	s_add_i32 s7, s84, s7
	s_add_i32 s16, s7, 0xdffff80
	v_or_b32_e32 v0, s40, v200
	s_cmp_gt_i32 s7, 0
	v_lshlrev_b32_e32 v157, 1, v0
	s_cselect_b32 s17, 0, 0xffffff80
	v_add_u32_e32 v0, s17, v157
	s_cselect_b32 s16, s16, 0xe000000
	s_add_i32 s7, s7, 0xe000000
	s_addk_i32 s6, 0x2800
	buffer_load_dwordx2 v[176:177], v0, s[52:55], s16 offen
	buffer_load_dwordx2 v[178:179], v157, s[52:55], s7 offen
	buffer_load_dwordx4 v[100:103], v202, s[52:55], s6 offen sc1
	v_readlane_b32 s6, v254, 0
	s_add_u32 s85, s6, s2
	v_readlane_b32 s2, v254, 2
	v_mov_b32_e32 v2, v1
	v_mov_b32_e32 v3, v1
	s_addc_u32 s86, s2, s3
	v_mov_b32_e32 v0, v1
	v_mov_b64_e32 v[58:59], v[2:3]
	v_readlane_b32 s2, v254, 42
	s_mov_b32 s95, s45
	v_mov_b64_e32 v[56:57], v[0:1]
	s_mov_b32 s72, s2
	v_readlane_b32 s3, v254, 43
	s_lshl_b32 s100, s72, 11
	s_add_i32 s100, s100, s84
	s_add_i32 s101, s100, 0xe002000
	buffer_load_dwordx2 v[184:185], v157, s[52:55], s101 offen
	s_add_i32 s101, s100, 0xe001f80
	buffer_load_dwordx2 v[182:183], v157, s[52:55], s101 offen
	s_lshl_b32 s100, s72, 11
	s_add_i32 s100, s100, s84
	s_add_i32 s101, s100, 0xe004000
	buffer_load_dwordx2 v[234:235], v157, s[52:55], s101 offen
	s_add_i32 s101, s100, 0xe003f80
	buffer_load_dwordx2 v[232:233], v157, s[52:55], s101 offen
	s_add_i32 s101, s100, 0xe006000
	buffer_load_dwordx2 v[238:239], v157, s[52:55], s101 offen
	s_add_i32 s101, s100, 0xe005f80
	buffer_load_dwordx2 v[236:237], v157, s[52:55], s101 offen
	s_lshl_b32 s100, s72, 2
	s_add_u32 s100, s82, s100
	s_addc_u32 s101, s83, 0
	global_load_dword v229, v1, s[100:101] offset:16 sc1
	global_load_dword v230, v1, s[100:101] offset:32 sc1
	s_mov_b32 s99, 0
	s_mov_b32 s32, 0
	v_mov_b32_e32 v2, 0
	s_ashr_i32 s2, s81, 7
	v_readlane_b32 s3, v254, 40
	s_add_i32 s3, s2, s3
	s_lshl_b32 s16, s3, 6
	s_lshr_b32 s100, s51, 2
	s_lshl_b32 s100, s100, 11
	s_or_b32 s16, s16, s100
	s_and_b32 s100, s51, 3
	s_lshl_b32 s100, s100, 9
	s_or_b32 s16, s16, s100
	s_cmp_lt_i32 s2, s48
	s_cselect_b64 s[46:47], -1, 0
	s_cmp_lt_i32 s3, s20
	s_cselect_b64 s[60:61], -1, 0
	s_ashr_i32 s2, s16, 16
	s_ashr_i32 s3, s2, 31
	s_bfe_u32 s17, s16, 0x5000b
	s_lshl_b64 s[18:19], s[2:3], 12
	s_lshl_b32 s2, s2, 12
	s_or_b32 s88, s18, s17
	s_or_b32 s87, s2, s17
	s_cmp_lt_i32 s81, s56
	s_cselect_b64 s[2:3], -1, 0
	v_or_b32_e32 v0, s16, v165
	s_and_b64 s[2:3], s[2:3], s[46:47]
	v_cmp_gt_i32_e32 vcc, s55, v0
	s_and_b64 s[2:3], s[2:3], s[60:61]
	s_and_b64 s[58:59], s[2:3], vcc
	s_lshl_b32 s2, s81, 5
	v_lshlrev_b32_e32 v0, 3, v0
	s_and_b32 s16, s2, 0xf80
	v_and_b32_e32 v0, 0x3f00, v0
	s_or_b32 s18, s88, s16
	v_lshl_add_u64 v[104:105], v[154:155], 0, v[0:1]
	s_lshl_b64 s[2:3], s[18:19], 14
	v_lshl_add_u64 v[158:159], v[104:105], 0, s[2:3]
	v_mov_b32_e32 v162, 0
	v_mov_b32_e32 v163, 0
	s_and_saveexec_b64 s[2:3], s[58:59]
	s_cbranch_execz .Lssd2p_687
	s_add_i32 s32, s32, 2
	s_or_b32 s16, s87, s16
	s_ashr_i32 s17, s16, 31
	s_lshl_b64 s[16:17], s[16:17], 2
	v_readlane_b32 s62, v253, 54
	v_readlane_b32 s63, v253, 55
	s_add_u32 s16, s62, s16
	s_addc_u32 s17, s63, s17
	global_load_dwordx2 v[162:163], v[158:159], off
	global_load_dword v2, v1, s[16:17]

; #define RD_PEEK(cc) __hip_atomic_load(READY + bh * 512 + (cc), __ATOMIC_RELAXED, __HIP_MEMORY_SCOPE_AGENT)
; __device__ void phase_rwkv_dist(const Params& p, LAS unsigned char* lds, int wg, int nwg) {
;     ...
;             for (int c2 = fw; c2 < RC_NCHK; c2 += 8) {
;                 const unsigned pr1 = RD_PEEK(c2 + 4), pr0 = (c2 + 8 < RC_NCHK) ? RD_PEEK(c2 + 8) : 0u;
;                 u32x2 raw[4]; float dd[4]; bf16_t* qq[4]; bool ok[4];
; #pragma unroll
;                 for (int k = 0; k < 4; ++k) { const int ss = s2 + k, item = fw * per + (ss >> 7), cc = ss & 127, idx = item * (nwg * 64) + wg * 64 + lane; ok[k] = ss < nstep && (ss >> 7) < per && item < nitem && idx < BATCH * 32 * 64 * 32;
;                     const int n4 = idx & 31, pp = (idx >> 5) & 63, eg = (idx >> 11) & 31, bb = idx >> 16;
;                     qq[k] = SS + ((((size_t)bb * 128 + cc) * 32 + eg) * 64 + pp) * 128 + 4 * n4; raw[k] = (u32x2){0u, 0u}; dd[k] = 0.f;
;                     if (ok[k]) { raw[k] = *(const u32x2*)qq[k]; dd[k] = CD[(bb * 128 + cc) * 32 + eg]; } }
;                 RD_ISSUE(c2 + 4, 1, pr1);
.LBB0_683:
	s_lshl_b64 s[40:41], s[72:73], 2
	s_add_u32 s6, s82, s40
	s_addc_u32 s7, s83, s41
	s_cmpk_lt_i32 s72, 0x1f8
	s_cselect_b64 s[44:45], -1, 0
	s_cmpk_gt_i32 s72, 0x1f7
	s_cselect_b64 s[38:39], -1, 0
	s_and_b64 vcc, exec, s[38:39]
	v_mov_b32_e32 v3, 0
	s_add_i32 s100, s99, s32
	s_cmp_eq_u32 s100, 18
	s_cbranch_scc1 .Lfetch_w18
	s_cmp_eq_u32 s100, 16
	s_cbranch_scc1 .Lfetch_w16
	s_cmp_eq_u32 s100, 14
	s_cbranch_scc1 .Lfetch_w14
	s_cmp_eq_u32 s100, 13
	s_cbranch_scc1 .Lfetch_w13
	s_cmp_eq_u32 s100, 8
	s_cbranch_scc1 .Lfetch_w8
	s_waitcnt vmcnt(0)
	s_branch .Lfetch_wd
.Lfetch_w18:
	s_waitcnt vmcnt(18)
	s_branch .Lfetch_wd
.Lfetch_w16:
	s_waitcnt vmcnt(16)
	s_branch .Lfetch_wd

; __device__ void phase_rwkv_dist(const Params& p, LAS unsigned char* lds, int wg, int nwg) {
;     ...
;                 RD_ISSUE(c2 + 4, 1, pr1);
.LBB0_713:
	s_add_i32 s87, s72, 4
	s_lshr_b32 s16, s87, 3
	s_mul_hi_u32 s16, s16, 0x24924925
	s_mul_i32 s16, s16, 56
	s_sub_i32 s16, s87, s16
	s_mulk_i32 s16, 0x2900
	s_add_i32 s16, s16, s80
	s_add_i32 s18, s16, 0x2000
	s_add_i32 s17, s16, 0x1000
	buffer_load_dwordx4 v[116:119], v196, s[52:55], s16 offen sc1
	buffer_load_dwordx4 v[104:107], v196, s[52:55], s17 offen sc1
	buffer_load_dwordx4 v[112:115], v215, s[52:55], s16 offen sc1
	buffer_load_dwordx4 v[108:111], v213, s[52:55], s17 offen sc1
	buffer_load_dwordx4 v[136:139], v197, s[52:55], s16 offen sc1
	buffer_load_dwordx4 v[120:123], v196, s[52:55], s18 offen sc1
	buffer_load_dwordx4 v[132:135], v197, s[52:55], s17 offen sc1
	buffer_load_dwordx4 v[124:127], v197, s[52:55], s18 offen sc1
	s_add_i32 s18, s16, 0x2800
	buffer_load_dwordx4 v[140:143], v213, s[52:55], s16 offen sc1
	buffer_load_dwordx4 v[128:131], v202, s[52:55], s18 offen sc1
	s_lshl_b32 s16, s87, 11
	s_add_i32 s16, s16, s84
	s_add_i32 s18, s16, 0xe000000
	s_add_i32 s19, s16, 0xdffff80
	s_cmp_gt_i32 s16, 0
	s_cselect_b32 s16, 0, 0xffffff80
	s_cselect_b32 s16, s19, 0xe000000
	buffer_load_dwordx4 v[144:147], v215, s[52:55], s17 offen sc1
	s_mov_b64 s[46:47], -1
	s_and_b64 vcc, exec, s[42:43]
	s_cbranch_vccnz .LBB0_723
	s_add_i32 s42, s72, -11
	s_mov_b32 s43, 0
	s_branch .LBB0_716

; __device__ void phase_rwkv_dist(const Params& p, LAS unsigned char* lds, int wg, int nwg) {
;     ...
;                 RD_ISSUE(c2 + 4, 1, pr1);
;                 RD_STAGE(c2, 0);
;                 if (c2 + 8 < RC_NCHK) RD_ISSUE(c2 + 8, 0, pr0);
;                 RD_STAGE(c2 + 4, 1);
.LBB0_725:
	s_mov_b32 s98, 0
	s_mov_b32 s99, 0
	s_mov_b64 s[42:43], -1
	s_and_b64 vcc, exec, s[46:47]
	s_cbranch_vccz .LBB0_748
	s_branch .LBB0_757

.LBB0_747:
	s_lshr_b32 s6, s44, 3
	s_mul_hi_u32 s6, s6, 0x24924925
	s_mul_i32 s6, s6, 56
	s_sub_i32 s6, s44, s6
	s_mulk_i32 s6, 0x2900
	s_add_i32 s6, s6, s80
	s_add_i32 s7, s6, 0x1000
	buffer_load_dwordx4 v[76:79], v196, s[52:55], s6 offen sc1
	buffer_load_dwordx4 v[68:71], v197, s[52:55], s6 offen sc1
	buffer_load_dwordx4 v[60:63], v213, s[52:55], s6 offen sc1
	buffer_load_dwordx4 v[64:67], v215, s[52:55], s6 offen sc1
	buffer_load_dwordx4 v[92:95], v196, s[52:55], s7 offen sc1
	buffer_load_dwordx4 v[96:99], v197, s[52:55], s7 offen sc1
	buffer_load_dwordx4 v[84:87], v213, s[52:55], s7 offen sc1
	buffer_load_dwordx4 v[88:91], v215, s[52:55], s7 offen sc1
	s_add_i32 s7, s6, 0x2000
	s_addk_i32 s6, 0x2800
	buffer_load_dwordx4 v[72:75], v196, s[52:55], s7 offen sc1
	buffer_load_dwordx4 v[80:83], v197, s[52:55], s7 offen sc1
	buffer_load_dwordx4 v[100:103], v202, s[52:55], s6 offen sc1
	s_lshl_b32 s6, s44, 11
	s_add_i32 s6, s6, s84
	s_add_i32 s7, s6, 0xe000000
	s_add_i32 s16, s6, 0xdffff80
	s_cmp_gt_i32 s6, 0
	s_cselect_b32 s6, 0, 0xffffff80
	v_add_u32_e32 v3, s6, v157
	s_cselect_b32 s6, s16, 0xe000000
	s_lshl_b32 s100, s72, 2
	s_add_u32 s100, s82, s100
	s_addc_u32 s101, s83, 0
	global_load_dword v229, v1, s[100:101] offset:48 sc1
	s_mov_b32 s98, 12
	v_mov_b32_e32 v230, 0
	s_cmpk_gt_i32 s72, 0x1ef
	s_cbranch_scc1 .Lfetch_nop0
	global_load_dword v230, v1, s[100:101] offset:64 sc1
	s_mov_b32 s98, 13
.Lfetch_nop0:
	s_mov_b32 s99, 0
	s_cmp_lt_u32 s72, 8
	s_cbranch_scc1 .Lfetch_nodone
	s_mov_b64 s[100:101], exec
	v_mbcnt_lo_u32_b32 v231, s100, 0
	v_mbcnt_hi_u32_b32 v231, s101, v231
	v_cmp_eq_u32_e32 vcc, 0, v231
	s_and_saveexec_b64 s[100:101], vcc
	v_mov_b32_e32 v231, 64
	global_atomic_add v1, v231, s[40:41] offset:-32
	global_atomic_add v1, v231, s[40:41] offset:-16
	s_or_b64 exec, exec, s[100:101]
	s_add_i32 s98, s98, 2
	s_mov_b32 s99, 2

; __device__ void phase_rwkv_dist(const Params& p, LAS unsigned char* lds, int wg, int nwg) {
;     ...
;                 RD_STAGE(c2 + 4, 1);
.LBB0_757:
	s_cmp_eq_u32 s98, 15
	s_cbranch_scc1 .Lfetch_s6w15
	s_cmp_eq_u32 s98, 14
	s_cbranch_scc1 .Lfetch_s6w14
	s_cmp_eq_u32 s98, 13
	s_cbranch_scc1 .Lfetch_s6w13
	s_cmp_eq_u32 s98, 12
	s_cbranch_scc1 .Lfetch_s6w12
	s_cmp_eq_u32 s98, 16
	s_cbranch_scc1 .Lfetch_s6w16
	s_cmp_eq_u32 s98, 17
	s_cbranch_scc1 .Lfetch_s6w17
	s_waitcnt vmcnt(0)
	s_branch .Lfetch_s6wd
.Lfetch_s6w15:
	s_waitcnt vmcnt(15)
	s_branch .Lfetch_s6wd
.Lfetch_s6w14:
	s_waitcnt vmcnt(14)
	s_branch .Lfetch_s6wd

.Lfetch_s6w12:
	s_waitcnt vmcnt(12)
	s_branch .Lfetch_s6wd

.Lfetch_s6w17:
	s_waitcnt vmcnt(17)
	s_branch .Lfetch_s6wd
.Lfetch_s6wd:
	v_mov_b64_e32 v[176:177], v[232:233]
	v_mov_b64_e32 v[178:179], v[234:235]
	v_mov_b64_e32 v[240:241], v[236:237]
	v_mov_b64_e32 v[242:243], v[238:239]
	s_cmpk_lt_i32 s72, 0x1f0
	s_cbranch_scc0 .Lfetch_nopv
	s_lshl_b32 s100, s72, 11
	s_add_i32 s100, s100, s84
	s_add_i32 s101, s100, 0xe008000
	buffer_load_dwordx2 v[234:235], v157, s[52:55], s101 offen
	s_add_i32 s101, s100, 0xe007f80
	buffer_load_dwordx2 v[232:233], v157, s[52:55], s101 offen
	s_add_i32 s99, s99, 2
	s_cmpk_lt_i32 s72, 0x1ec
	s_cbranch_scc0 .Lfetch_nopv
	s_add_i32 s101, s100, 0xe00a000
	buffer_load_dwordx2 v[238:239], v157, s[52:55], s101 offen
	s_add_i32 s101, s100, 0xe009f80
	buffer_load_dwordx2 v[236:237], v157, s[52:55], s101 offen
	s_add_i32 s99, s99, 2
.Lfetch_nopv:
	v_lshlrev_b32_e32 v220, 16, v184
	v_and_b32_e32 v221, 0xffff0000, v184
	v_lshlrev_b32_e32 v184, 16, v185
	v_and_b32_e32 v185, 0xffff0000, v185
	v_lshlrev_b32_e32 v3, 16, v182
	v_and_b32_e32 v182, 0xffff0000, v182
	v_lshlrev_b32_e32 v195, 16, v183
	v_and_b32_e32 v222, 0xffff0000, v183
	s_mul_hi_u32 s6, s87, 0xaaaaaaab
	v_sub_f32_e32 v183, v182, v221
	v_sub_f32_e32 v182, v3, v220
	v_sub_f32_e32 v223, v222, v185
	v_sub_f32_e32 v222, v195, v184
	s_lshr_b32 s6, s6, 3
	v_pk_fma_f32 v[184:185], v[54:55], v[222:223], v[184:185]
	v_pk_fma_f32 v[182:183], v[52:53], v[182:183], v[220:221]
	s_mul_i32 s6, s6, 12
	v_cvt_pk_bf16_f32 v182, v182, v183
	v_cvt_pk_bf16_f32 v183, v184, v185
	s_sub_i32 s6, s87, s6
	s_mul_i32 s7, s6, 0x2b00
	s_add_i32 s7, s7, 0
	v_add_u32_e32 v3, s7, v196
	ds_write_b128 v3, v[116:119]
	ds_write_b128 v3, v[136:139] offset:1024
	ds_write_b128 v3, v[140:143] offset:2048
	ds_write_b128 v3, v[112:115] offset:3072
	ds_write_b128 v3, v[104:107] offset:4096
	ds_write_b128 v3, v[132:135] offset:5120
	ds_write_b128 v3, v[108:111] offset:6144
	ds_write_b128 v3, v[144:147] offset:7168
	ds_write_b128 v3, v[120:123] offset:8192
	ds_write_b128 v3, v[124:127] offset:9216
	v_mfma_f32_16x16x16_bf16 v[104:107], v[182:183], v[150:151], 0
	v_mov_b64_e32 v[182:183], v[240:241]
	v_mov_b64_e32 v[184:185], v[242:243]
	s_lshl_b32 s6, s6, 2
	v_add_u32_e32 v3, s7, v202
	s_add_i32 s6, s6, 0
	ds_write_b128 v3, v[128:131] offset:10752
	v_add_u32_e32 v3, s7, v203
	s_nop 2
	v_cvt_pk_bf16_f32 v104, v104, v105
	v_cvt_pk_bf16_f32 v105, v106, v107
	s_add_i32 s7, s72, 5
	s_add_i32 s6, s6, 0x27400
	ds_write_b64 v3, v[104:105] offset:10240
	v_mov_b32_e32 v3, s6
	v_mov_b32_e32 v104, s7
	s_mov_b64 s[6:7], exec
	s_waitcnt lgkmcnt(0)
	ds_write_b32 v3, v104
	v_mbcnt_lo_u32_b32 v3, s6, 0
	v_mbcnt_hi_u32_b32 v3, s7, v3
	v_cmp_eq_u32_e32 vcc, 0, v3
	s_and_saveexec_b64 s[16:17], vcc
	s_cbranch_execz .LBB0_759
	s_bcnt1_i32_b64 s6, s[6:7]
	v_mov_b32_e32 v3, s6
